# scan step C: the four per-timestep bonus wave-sums interleaved 4-way (no dependent s_nop stalls) and the step-loop operand prefetch hoisted above them
# speedup vs baseline: 1.0053x; 1.0020x over previous
; DI float lo2f(unsigned u) { return __uint_as_float(u << 16); }
; DI float hi2f(unsigned u) { return __uint_as_float(u & 0xffff0000u); }
; DI void item_scan(const Params& p, int l, int L, int b, int h, int dir, const bf16_t* __restrict__ z, bf16_t* __restrict__ yout, float* __restrict__ bon, unsigned char* smem) {
;     ...
;       const int tt = tid >> 4, j = tid & 15, c = 4 * j;
;       u32x2 zu[5][3];
;       f32x4 mm[5][2];
; #pragma unroll
;       for (int s5 = 0; s5 < 5; ++s5) {
; #pragma unroll
;         for (int d3 = 0; d3 < 3; ++d3) zu[s5][d3] = *(const u32x2*)(ZR + (tt + d3) * 160 + s5 * 32 + 2 * j);
;         mm[s5][0] = *(const f32x4*)(MU + (s5 * 2) * 64 + c);
;         mm[s5][1] = *(const f32x4*)(MU + (s5 * 2 + 1) * 64 + c);
;       }
;       float zs[5][4];
; #pragma unroll
;       for (int s5 = 0; s5 < 5; ++s5)
; #pragma unroll
;         for (int e = 0; e < 4; ++e) {
;           const unsigned up = zu[s5][0][e >> 1], uc = zu[s5][1][e >> 1], un = zu[s5][2][e >> 1];
;           const float pv = (e & 1) ? hi2f(up) : lo2f(up), cv = (e & 1) ? hi2f(uc) : lo2f(uc), nv = (e & 1) ? hi2f(un) : lo2f(un);
;           zs[s5][e] = cv + mm[s5][0][e] * (pv - cv) + mm[s5][1][e] * (nv - cv);
;         }
.LBB0_513:
	ds_read2_b64 v[16:19], v141 offset1:16
	ds_read2_b64 v[20:23], v141 offset0:64 offset1:80
	ds_read2_b64 v[24:27], v141 offset0:160 offset1:176
	ds_read2_b64 v[28:31], v141 offset0:96 offset1:112
	ds_read_b128 v[32:35], v150 offset:45120
	ds_read_b128 v[36:39], v150 offset:45376
	ds_read2_b64 v[46:49], v141 offset0:32 offset1:48
	ds_read2_b64 v[60:63], v141 offset0:192 offset1:208
	ds_read_b128 v[90:93], v150 offset:45632
	ds_read_b128 v[94:97], v150 offset:45888
	ds_read2_b64 v[98:101], v141 offset0:128 offset1:144
	ds_read_b128 v[102:105], v150 offset:46144
	ds_read_b128 v[156:159], v150 offset:46400
	ds_read_b128 v[160:163], v150 offset:44864
	ds_read_b64 v[50:51], v141 offset:1792
	ds_read_b128 v[164:167], v150 offset:46656
	ds_read_b128 v[168:171], v150 offset:46912
	ds_read_b128 v[172:175], v150 offset:47168
	s_waitcnt lgkmcnt(14)
	v_lshlrev_b32_e32 v106, 16, v16
	v_and_b32_e32 v107, 0xffff0000, v16
	v_lshlrev_b32_e32 v176, 16, v22
	v_and_b32_e32 v177, 0xffff0000, v22
	v_lshlrev_b32_e32 v16, 16, v17
	v_and_b32_e32 v17, 0xffff0000, v17
	v_lshlrev_b32_e32 v22, 16, v23
	v_and_b32_e32 v23, 0xffff0000, v23
	v_lshlrev_b32_e32 v178, 16, v24
	v_and_b32_e32 v179, 0xffff0000, v24
	v_lshlrev_b32_e32 v24, 16, v25
	v_and_b32_e32 v25, 0xffff0000, v25
	v_pk_add_f32 v[16:17], v[16:17], v[22:23] neg_lo:[0,1] neg_hi:[0,1]
	v_pk_add_f32 v[106:107], v[106:107], v[176:177] neg_lo:[0,1] neg_hi:[0,1]
	s_waitcnt lgkmcnt(4)
	v_pk_fma_f32 v[16:17], v[162:163], v[16:17], v[22:23]
	v_pk_add_f32 v[22:23], v[24:25], v[22:23] neg_lo:[0,1] neg_hi:[0,1]
	v_lshlrev_b32_e32 v24, 16, v26
	v_pk_fma_f32 v[34:35], v[34:35], v[22:23], v[16:17]
	v_lshlrev_b32_e32 v16, 16, v18
	v_and_b32_e32 v17, 0xffff0000, v18
	v_lshlrev_b32_e32 v22, 16, v28
	v_and_b32_e32 v23, 0xffff0000, v28
	v_and_b32_e32 v25, 0xffff0000, v26
	v_pk_add_f32 v[16:17], v[16:17], v[22:23] neg_lo:[0,1] neg_hi:[0,1]
	v_lshlrev_b32_e32 v18, 16, v19
	v_pk_fma_f32 v[16:17], v[36:37], v[16:17], v[22:23]
	v_pk_add_f32 v[22:23], v[24:25], v[22:23] neg_lo:[0,1] neg_hi:[0,1]
	v_and_b32_e32 v19, 0xffff0000, v19
	v_pk_fma_f32 v[16:17], v[90:91], v[22:23], v[16:17]
	v_lshlrev_b32_e32 v22, 16, v29
	v_and_b32_e32 v23, 0xffff0000, v29
	v_lshlrev_b32_e32 v24, 16, v27
	v_and_b32_e32 v25, 0xffff0000, v27
	v_pk_add_f32 v[18:19], v[18:19], v[22:23] neg_lo:[0,1] neg_hi:[0,1]
	v_lshlrev_b32_e32 v26, 16, v60
	v_pk_fma_f32 v[18:19], v[38:39], v[18:19], v[22:23]
	v_pk_add_f32 v[22:23], v[24:25], v[22:23] neg_lo:[0,1] neg_hi:[0,1]
	v_lshlrev_b32_e32 v24, 16, v30
	v_pk_fma_f32 v[18:19], v[92:93], v[22:23], v[18:19]
	v_lshlrev_b32_e32 v22, 16, v46
	v_and_b32_e32 v23, 0xffff0000, v46
	v_and_b32_e32 v25, 0xffff0000, v30
	v_and_b32_e32 v27, 0xffff0000, v60
	v_pk_add_f32 v[22:23], v[22:23], v[24:25] neg_lo:[0,1] neg_hi:[0,1]
	v_lshlrev_b32_e32 v28, 16, v61
	v_pk_fma_f32 v[22:23], v[94:95], v[22:23], v[24:25]
	v_pk_add_f32 v[24:25], v[26:27], v[24:25] neg_lo:[0,1] neg_hi:[0,1]
	v_lshlrev_b32_e32 v26, 16, v31
	v_pk_fma_f32 v[22:23], v[102:103], v[24:25], v[22:23]
	v_lshlrev_b32_e32 v24, 16, v47
	v_and_b32_e32 v25, 0xffff0000, v47
	v_and_b32_e32 v27, 0xffff0000, v31
	v_and_b32_e32 v29, 0xffff0000, v61
	v_pk_add_f32 v[24:25], v[24:25], v[26:27] neg_lo:[0,1] neg_hi:[0,1]
	v_mov_b32_e32 v30, v156
	v_pk_fma_f32 v[24:25], v[96:97], v[24:25], v[26:27]
	v_pk_add_f32 v[26:27], v[28:29], v[26:27] neg_lo:[0,1] neg_hi:[0,1]
	v_lshlrev_b32_e32 v29, 16, v62
	v_pk_fma_f32 v[24:25], v[104:105], v[26:27], v[24:25]
	v_lshlrev_b32_e32 v26, 16, v98
	v_lshlrev_b32_e32 v28, 16, v48
	v_pk_add_f32 v[28:29], v[28:29], v[26:27] op_sel_hi:[1,0] neg_lo:[0,1] neg_hi:[0,1]
	s_waitcnt lgkmcnt(2)
	v_mov_b32_e32 v31, v164
	v_pk_mul_f32 v[28:29], v[30:31], v[28:29]
	v_mov_b32_e32 v164, v157
	v_add_f32_e32 v26, v28, v26
	v_add_f32_e32 v46, v26, v29
	v_and_b32_e32 v26, 0xffff0000, v98
	v_and_b32_e32 v29, 0xffff0000, v62
	v_and_b32_e32 v28, 0xffff0000, v48
	v_pk_add_f32 v[28:29], v[28:29], v[26:27] op_sel_hi:[1,0] neg_lo:[0,1] neg_hi:[0,1]
	v_mov_b32_e32 v30, v158
	v_pk_mul_f32 v[28:29], v[164:165], v[28:29]
	v_mov_b32_e32 v31, v166
	v_add_f32_e32 v26, v28, v26
	v_add_f32_e32 v47, v26, v29
	v_lshlrev_b32_e32 v26, 16, v99
	v_lshlrev_b32_e32 v29, 16, v63
	v_lshlrev_b32_e32 v28, 16, v49
	v_pk_add_f32 v[28:29], v[28:29], v[26:27] op_sel_hi:[1,0] neg_lo:[0,1] neg_hi:[0,1]
	v_mov_b32_e32 v166, v159
	v_pk_mul_f32 v[28:29], v[30:31], v[28:29]
	v_lshlrev_b32_e32 v30, 16, v50
	v_add_f32_e32 v26, v28, v26
	v_add_f32_e32 v48, v26, v29
	v_and_b32_e32 v26, 0xffff0000, v99
	v_and_b32_e32 v29, 0xffff0000, v63
	v_and_b32_e32 v28, 0xffff0000, v49
	v_pk_add_f32 v[28:29], v[28:29], v[26:27] op_sel_hi:[1,0] neg_lo:[0,1] neg_hi:[0,1]
	v_and_b32_e32 v27, 0xffff0000, v20
	v_pk_mul_f32 v[28:29], v[166:167], v[28:29]
	v_and_b32_e32 v31, 0xffff0000, v50
	v_add_f32_e32 v26, v28, v26
	v_add_f32_e32 v49, v26, v29
	v_lshlrev_b32_e32 v26, 16, v20
	v_lshlrev_b32_e32 v28, 16, v100
	v_and_b32_e32 v29, 0xffff0000, v100
	v_pk_add_f32 v[26:27], v[26:27], v[28:29] neg_lo:[0,1] neg_hi:[0,1]
	v_add_u32_e32 v20, v133, v132
	s_waitcnt lgkmcnt(1)
	v_pk_fma_f32 v[36:37], v[168:169], v[26:27], v[28:29]
	v_pk_add_f32 v[30:31], v[30:31], v[28:29] neg_lo:[0,1] neg_hi:[0,1]
	ds_read_b128 v[26:29], v20 offset:47424
	v_pk_fma_f32 v[106:107], v[160:161], v[106:107], v[176:177]
	v_pk_add_f32 v[160:161], v[178:179], v[176:177] neg_lo:[0,1] neg_hi:[0,1]
	s_waitcnt lgkmcnt(1)
; #define MFMA16(a, b, c) __builtin_amdgcn_mfma_f32_16x16x32_bf16((a), (b), (c), 0, 0, 0)
; DI unsigned pack2(float lo, float hi) { const f32x2 v = {lo, hi}; const bf16x2_t b = __builtin_convertvector(v, bf16x2_t); return __builtin_bit_cast(unsigned, b); }
; DI void item_scan(const Params& p, int l, int L, int b, int h, int dir, const bf16_t* __restrict__ z, bf16_t* __restrict__ yout, float* __restrict__ bon, unsigned char* smem) {
;     ...
;       *(f32x4*)(VR + tt * 64 + c) = (f32x4){zs[0][0], zs[0][1], zs[0][2], zs[0][3]};
;       *(f32x4*)(VK + tt * 64 + c) = (f32x4){zs[1][0], zs[1][1], zs[1][2], zs[1][3]};
;       *(f32x4*)(VV + tt * 64 + c) = (f32x4){zs[2][0], zs[2][1], zs[2][2], zs[2][3]};
;       const f32x4 kc = *(const f32x4*)(KKC + c);
;       float kq4[4], th[4];
;       float ksum = 0.f;
; #pragma unroll
;       for (int e = 0; e < 4; ++e) {
;         kq4[e] = zs[1][e] * kc[e];
;         ksum += kq4[e] * kq4[e];
;         th[e] = 1.0f - 2.0f * rcp_(__expf(2.0f * zs[3][e]) + 1.0f);
;       }
;       *(u32x2*)(WT + tt * RS + c * 2) = (u32x2){pack2(th[0], th[1]), pack2(th[2], th[3])};
;       *(u32x2*)(AL + tt * RS + c * 2) = (u32x2){pack2(zs[4][0], zs[4][1]), pack2(zs[4][2], zs[4][3])};
;       ksum = row_sum16(ksum);
;       const float inv = rcp_(fmaxf(sqrtf(ksum), 1e-12f));
;       *(f32x4*)(VA + tt * 64 + c) = (f32x4){kq4[0] * inv, kq4[1] * inv, kq4[2] * inv, kq4[3] * inv};
;     }
;     __syncthreads();
;     {
;       f32x4 aw = {0.f, 0.f, 0.f, 0.f}, aa = {0.f, 0.f, 0.f, 0.f};
; #pragma unroll
;       for (int ks = 0; ks < 2; ++ks) {
;         const bf16x8 fw = *(const bf16x8*)(WT + fr * RS + ks * 64 + fq * 16);
;         const bf16x8 fa = *(const bf16x8*)(AL + fr * RS + ks * 64 + fq * 16);
;         aw = MFMA16(fw, bw[ks], aw);
;         aa = MFMA16(fa, ba[ks], aa);
;       }
; #pragma unroll
;       for (int j = 0; j < 4; ++j) {
;         const int tt = fq * 4 + j;
;         const float x = w0c + aw[j];
;         const float e = 0.60653065971263342f * sigmoidf_(x);
;         const float dcy = __expf(-e);
;         const float a = sigmoidf_(a0c + aa[j]);
;         const float k = VK[tt * 64 + cB], kk = VA[tt * 64 + cB];
;         VD[tt * 64 + cB] = dcy;
;         VK[tt * 64 + cB] = k * (1.0f + (a - 1.0f) * kac);
;         VA[tt * 64 + cB] = -kk;
;         VB[tt * 64 + cB] = kk * a;
;       }
;     }
;     __syncthreads();
	v_pk_fma_f32 v[30:31], v[172:173], v[30:31], v[36:37]
	v_pk_fma_f32 v[32:33], v[32:33], v[160:161], v[106:107]
	v_lshlrev_b32_e32 v20, 16, v21
	v_and_b32_e32 v21, 0xffff0000, v21
	v_lshlrev_b32_e32 v36, 16, v101
	v_and_b32_e32 v37, 0xffff0000, v101
	v_lshlrev_b32_e32 v38, 16, v51
	v_and_b32_e32 v39, 0xffff0000, v51
	v_pk_add_f32 v[20:21], v[20:21], v[36:37] neg_lo:[0,1] neg_hi:[0,1]
	ds_write_b128 v134, v[32:35] offset:11520
	ds_write_b128 v134, v[16:19] offset:19712
	ds_write_b128 v134, v[22:25] offset:23808
	s_waitcnt lgkmcnt(3)
	v_pk_mul_f32 v[16:17], v[16:17], v[26:27]
	v_pk_fma_f32 v[20:21], v[170:171], v[20:21], v[36:37]
	v_pk_add_f32 v[36:37], v[38:39], v[36:37] neg_lo:[0,1] neg_hi:[0,1]
	v_pk_mul_f32 v[26:27], v[16:17], v[16:17]
	v_pk_mul_f32 v[18:19], v[18:19], v[28:29]
	v_pk_fma_f32 v[20:21], v[174:175], v[36:37], v[20:21]
	v_add_f32_e32 v36, v46, v46
	v_add_f32_e32 v37, v47, v47
	v_add_f32_e32 v34, v48, v48
	v_add_f32_e32 v35, v49, v49
	v_pk_mul_f32 v[28:29], v[18:19], v[18:19]
	v_add_f32_e32 v26, v26, v27
	v_mul_f32_e32 v36, 0x3fb8aa3b, v36
	v_mul_f32_e32 v37, 0x3fb8aa3b, v37
	v_mul_f32_e32 v34, 0x3fb8aa3b, v34
	v_mul_f32_e32 v35, 0x3fb8aa3b, v35
	v_add_f32_e32 v26, v28, v26
	v_exp_f32_e32 v36, v36
	v_exp_f32_e32 v37, v37
	v_exp_f32_e32 v34, v34
	v_exp_f32_e32 v35, v35
	v_add_f32_e32 v26, v29, v26
	v_add_f32_e32 v32, 1.0, v36
	v_add_f32_e32 v33, 1.0, v37
	v_add_f32_dpp v26, v26, v26 quad_perm:[1,0,3,2] row_mask:0xf bank_mask:0xf bound_ctrl:1
	v_add_f32_e32 v34, 1.0, v34
	v_add_f32_e32 v35, 1.0, v35
	v_add_f32_dpp v26, v26, v26 quad_perm:[2,3,0,1] row_mask:0xf bank_mask:0xf bound_ctrl:1
	s_mov_b32 s12, 0xf800000
	v_rcp_f32_e32 v32, v32
	v_add_f32_dpp v26, v26, v26 row_half_mirror row_mask:0xf bank_mask:0xf bound_ctrl:1
	v_rcp_f32_e32 v33, v33
	v_rcp_f32_e32 v34, v34
	v_add_f32_dpp v26, v26, v26 row_mirror row_mask:0xf bank_mask:0xf bound_ctrl:1
	v_rcp_f32_e32 v35, v35
	v_mul_f32_e32 v27, 0x4f800000, v26
	v_cmp_gt_f32_e64 s[50:51], s12, v26
	v_pk_fma_f32 v[22:23], v[32:33], 2.0, 1.0 op_sel_hi:[1,0,0] neg_lo:[1,0,0] neg_hi:[1,0,0]
	v_pk_fma_f32 v[24:25], v[34:35], 2.0, 1.0 op_sel_hi:[1,0,0] neg_lo:[1,0,0] neg_hi:[1,0,0]
	v_cndmask_b32_e64 v26, v26, v27, s[50:51]
	v_sqrt_f32_e32 v27, v26
	v_cvt_pk_bf16_f32 v22, v22, v23
	v_cvt_pk_bf16_f32 v23, v24, v25
	ds_write_b64 v151, v[22:23] offset:40256
	v_add_u32_e32 v22, -1, v27
	v_fma_f32 v23, -v22, v27, v26
	v_cmp_ge_f32_e64 s[52:53], 0, v23
	v_add_u32_e32 v23, 1, v27
	v_fma_f32 v24, -v23, v27, v26
	v_cndmask_b32_e64 v22, v27, v22, s[52:53]
	v_cmp_lt_f32_e64 s[52:53], 0, v24
	v_cvt_pk_bf16_f32 v24, v30, v31
	v_cvt_pk_bf16_f32 v25, v20, v21
	v_cndmask_b32_e64 v22, v22, v23, s[52:53]
	v_mul_f32_e32 v23, 0x37800000, v22
	v_cndmask_b32_e64 v22, v22, v23, s[50:51]
	v_mov_b32_e32 v23, 0x260
	v_cmp_class_f32_e64 s[50:51], v26, v23
	ds_write_b64 v151, v[24:25] offset:42560
	s_nop 0
	v_cndmask_b32_e64 v22, v22, v26, s[50:51]
	v_max_f32_e32 v22, 0x2b8cbccc, v22
	v_rcp_f32_e32 v22, v22
	s_nop 0
	v_pk_mul_f32 v[18:19], v[18:19], v[22:23] op_sel_hi:[1,0]
	v_pk_mul_f32 v[16:17], v[16:17], v[22:23] op_sel_hi:[1,0]
	ds_write_b128 v134, v[16:19] offset:27904
	s_waitcnt lgkmcnt(0)
	s_barrier
	ds_read_b128 v[16:19], v152 offset:40256
	ds_read_b128 v[20:23], v152 offset:40320
	ds_read_b128 v[24:27], v152 offset:42560
	ds_read_b128 v[28:31], v152 offset:42624
	s_waitcnt lgkmcnt(3)
	v_mfma_f32_16x16x32_bf16 v[16:19], v[16:19], v[0:3], 0
	s_waitcnt lgkmcnt(1)
	v_mfma_f32_16x16x32_bf16 v[24:27], v[24:27], v[4:7], 0
	v_mfma_f32_16x16x32_bf16 v[16:19], v[20:23], v[8:11], v[16:19]
	s_waitcnt lgkmcnt(0)
	v_mfma_f32_16x16x32_bf16 v[20:23], v[28:31], v[12:15], v[24:27]
	s_nop 4
	ds_read2st64_b32 v[24:25], v142 offset0:77 offset1:78
	v_add_f32_e32 v16, v109, v16
	v_mul_f32_e32 v16, 0xbfb8aa3b, v16
	v_exp_f32_e32 v16, v16
	v_add_f32_e32 v20, v110, v20
	v_mul_f32_e32 v20, 0xbfb8aa3b, v20
	v_exp_f32_e32 v20, v20
	v_add_f32_e32 v16, 1.0, v16
	v_rcp_f32_e32 v16, v16
	v_add_f32_e32 v21, v110, v21
	v_add_f32_e32 v20, 1.0, v20
	v_rcp_f32_e32 v20, v20
	v_mul_f32_e32 v21, 0xbfb8aa3b, v21
	v_mul_f32_e32 v16, 0xbf1b4598, v16
	v_exp_f32_e32 v21, v21
	v_mul_f32_e32 v16, 0x3fb8aa3b, v16
	v_exp_f32_e32 v30, v16
	v_add_f32_e32 v16, -1.0, v20
	v_fma_f32 v31, v111, v16, 1.0
	v_add_f32_e32 v16, v109, v17
	v_mul_f32_e32 v16, 0xbfb8aa3b, v16
	v_add_f32_e32 v21, 1.0, v21
	v_exp_f32_e32 v32, v16
	v_rcp_f32_e32 v21, v21
	ds_read2st64_b32 v[16:17], v142 offset0:109 offset1:110
	ds_read2st64_b32 v[26:27], v142 offset0:111 offset1:112
	ds_read2st64_b32 v[28:29], v142 offset0:79 offset1:80
	v_add_f32_e32 v18, v109, v18
	v_mul_f32_e32 v18, 0xbfb8aa3b, v18
	s_waitcnt lgkmcnt(3)
	v_mul_f32_e32 v24, v24, v31
	v_add_f32_e32 v31, 1.0, v32
	s_waitcnt lgkmcnt(2)
	v_xor_b32_e32 v32, 0x80000000, v16
	v_mul_f32_e32 v16, v16, v20
	v_add_f32_e32 v20, -1.0, v21
	v_exp_f32_e32 v18, v18
	v_fma_f32 v20, v111, v20, 1.0
	v_mul_f32_e32 v20, v25, v20
	ds_write2st64_b32 v142, v24, v20 offset0:77 offset1:78
	v_xor_b32_e32 v20, 0x80000000, v17
	v_mul_f32_e32 v17, v21, v17
	ds_write2st64_b32 v142, v16, v17 offset0:125 offset1:126
	v_add_f32_e32 v16, 1.0, v18
	v_add_f32_e32 v18, v109, v19
	v_mul_f32_e32 v18, 0xbfb8aa3b, v18
	v_exp_f32_e32 v18, v18
	ds_write2st64_b32 v142, v32, v20 offset0:109 offset1:110
	v_add_f32_e32 v17, v110, v22
	v_add_f32_e32 v20, v110, v23
	v_add_f32_e32 v18, 1.0, v18
	v_rcp_f32_e32 v16, v16
	v_mul_f32_e32 v17, 0xbfb8aa3b, v17
	v_rcp_f32_e32 v18, v18
	v_mul_f32_e32 v20, 0xbfb8aa3b, v20
	v_exp_f32_e32 v17, v17
	v_exp_f32_e32 v20, v20
	v_mul_f32_e32 v16, 0xbf1b4598, v16
	v_mul_f32_e32 v18, 0xbf1b4598, v18
	v_rcp_f32_e32 v31, v31
	v_mul_f32_e32 v16, 0x3fb8aa3b, v16
	v_add_f32_e32 v17, 1.0, v17
	v_mul_f32_e32 v18, 0x3fb8aa3b, v18
	v_add_f32_e32 v20, 1.0, v20
	v_exp_f32_e32 v16, v16
	v_rcp_f32_e32 v17, v17
	v_exp_f32_e32 v18, v18
	v_rcp_f32_e32 v20, v20
	v_mul_f32_e32 v31, 0xbf1b4598, v31
	v_mul_f32_e32 v31, 0x3fb8aa3b, v31
	v_add_f32_e32 v19, -1.0, v17
	ds_write2st64_b32 v142, v16, v18 offset0:63 offset1:64
	v_add_f32_e32 v16, -1.0, v20
	v_exp_f32_e32 v31, v31
	v_fma_f32 v19, v111, v19, 1.0
	v_fma_f32 v16, v111, v16, 1.0
	s_waitcnt lgkmcnt(4)
	v_mul_f32_e32 v19, v19, v28
	v_mul_f32_e32 v16, v16, v29
	v_xor_b32_e32 v21, 0x80000000, v26
	ds_write2st64_b32 v142, v19, v16 offset0:79 offset1:80
	v_xor_b32_e32 v16, 0x80000000, v27
	v_mul_f32_e32 v17, v17, v26
	ds_write2st64_b32 v142, v21, v16 offset0:111 offset1:112
	v_mul_f32_e32 v16, v20, v27
	ds_write2st64_b32 v142, v30, v31 offset0:61 offset1:62
	ds_write2st64_b32 v142, v17, v16 offset0:127 offset1:128
	s_waitcnt lgkmcnt(0)
	s_barrier
; DI float wave_sum(float v) { return fq_sum(row_sum16(v)); }
; DI void item_scan(const Params& p, int l, int L, int b, int h, int dir, const bf16_t* __restrict__ z, bf16_t* __restrict__ yout, float* __restrict__ bon, unsigned char* smem) {
;     ...
;     float pc[4];
; #pragma unroll
;     for (int i = 0; i < 4; ++i) { const int tt = w * 4 + i; pc[i] = VR[tt * 64 + cA] * VK[tt * 64 + cA] * rkc; }
; #pragma unroll
;     for (int i = 0; i < 4; ++i) {
;       const int tt = w * 4 + i;
;       const float s = wave_sum(pc[i]);
;       if (lane == 0) BO[tt] = s;
;     }
;     ...
;       auto loada = [&](VA_& q, int off, int voff) {
;         q.A0 = *(const f32x4*)(VA + off); q.A1 = *(const f32x4*)(VA + off + 4);
;         q.V = *(const f32x2*)(VV + voff);
;       };
	ds_read2st64_b32 v[20:21], v143 offset0:45 offset1:46
	ds_read2st64_b32 v[22:23], v143 offset0:77 offset1:78
	ds_read2st64_b32 v[16:17], v143 offset0:79 offset1:80
	ds_read2st64_b32 v[18:19], v143 offset0:47 offset1:48
	s_waitcnt lgkmcnt(0)
	v_mul_f32_e32 v180, v20, v22
	v_mul_f32_e32 v184, v21, v23
	v_mul_f32_e32 v188, v18, v16
	v_mul_f32_e32 v192, v19, v17
	ds_read_b128 v[20:23], v138 offset:27904
	ds_read_b128 v[16:19], v138 offset:27920
	ds_read_b64 v[90:91], v139 offset:23808
	v_mul_f32_e32 v181, v83, v180
	v_mul_f32_e32 v185, v83, v184
	v_mul_f32_e32 v189, v83, v188
	v_mul_f32_e32 v193, v83, v192
	v_mov_b32_dpp v181, v181 quad_perm:[1,0,3,2] row_mask:0xf bank_mask:0xf bound_ctrl:1
	v_mov_b32_dpp v185, v185 quad_perm:[1,0,3,2] row_mask:0xf bank_mask:0xf bound_ctrl:1
	v_mov_b32_dpp v189, v189 quad_perm:[1,0,3,2] row_mask:0xf bank_mask:0xf bound_ctrl:1
	v_mov_b32_dpp v193, v193 quad_perm:[1,0,3,2] row_mask:0xf bank_mask:0xf bound_ctrl:1
	v_fmac_f32_e32 v181, v83, v180
	v_fmac_f32_e32 v185, v83, v184
	v_fmac_f32_e32 v189, v83, v188
	v_fmac_f32_e32 v193, v83, v192
	v_add_f32_dpp v180, v181, v181 quad_perm:[2,3,0,1] row_mask:0xf bank_mask:0xf bound_ctrl:1
	v_add_f32_dpp v184, v185, v185 quad_perm:[2,3,0,1] row_mask:0xf bank_mask:0xf bound_ctrl:1
	v_add_f32_dpp v188, v189, v189 quad_perm:[2,3,0,1] row_mask:0xf bank_mask:0xf bound_ctrl:1
	v_add_f32_dpp v192, v193, v193 quad_perm:[2,3,0,1] row_mask:0xf bank_mask:0xf bound_ctrl:1
	v_add_f32_dpp v180, v180, v180 row_half_mirror row_mask:0xf bank_mask:0xf bound_ctrl:1
	v_add_f32_dpp v184, v184, v184 row_half_mirror row_mask:0xf bank_mask:0xf bound_ctrl:1
	v_add_f32_dpp v188, v188, v188 row_half_mirror row_mask:0xf bank_mask:0xf bound_ctrl:1
	v_add_f32_dpp v192, v192, v192 row_half_mirror row_mask:0xf bank_mask:0xf bound_ctrl:1
	v_add_f32_dpp v180, v180, v180 row_mirror row_mask:0xf bank_mask:0xf bound_ctrl:1
	v_add_f32_dpp v184, v184, v184 row_mirror row_mask:0xf bank_mask:0xf bound_ctrl:1
	v_add_f32_dpp v188, v188, v188 row_mirror row_mask:0xf bank_mask:0xf bound_ctrl:1
	v_add_f32_dpp v192, v192, v192 row_mirror row_mask:0xf bank_mask:0xf bound_ctrl:1
	v_mov_b32_e32 v181, v180
	v_mov_b32_e32 v185, v184
	v_mov_b32_e32 v189, v188
	v_mov_b32_e32 v193, v192
	v_permlane16_swap_b32_e32 v180, v181
	v_permlane16_swap_b32_e32 v184, v185
	v_permlane16_swap_b32_e32 v188, v189
	v_permlane16_swap_b32_e32 v192, v193
	v_add_f32_e32 v180, v180, v181
	v_add_f32_e32 v184, v184, v185
	v_add_f32_e32 v188, v188, v189
	v_add_f32_e32 v192, v192, v193
	v_mov_b32_e32 v182, v180
	v_mov_b32_e32 v186, v184
	v_mov_b32_e32 v190, v188
	v_mov_b32_e32 v194, v192
	v_add_u32_e32 v196, s17, v108
	v_permlane32_swap_b32_e32 v180, v182
	v_permlane32_swap_b32_e32 v184, v186
	v_permlane32_swap_b32_e32 v188, v190
	v_permlane32_swap_b32_e32 v192, v194
	s_and_saveexec_b64 s[12:13], s[46:47]
	v_add_f32_e32 v180, v180, v182
	v_add_f32_e32 v184, v184, v186
	v_add_f32_e32 v188, v188, v190
	v_add_f32_e32 v192, v192, v194
	ds_write_b32 v196, v180 offset:40192
	ds_write_b32 v196, v184 offset:40196
	ds_write_b32 v196, v188 offset:40200
	ds_write_b32 v196, v192 offset:40204
	s_or_b64 exec, exec, s[12:13]
	s_mov_b32 s12, 8
	s_mov_b32 s13, s17
	s_waitcnt lgkmcnt(0)
	s_branch .LBB0_523
